# up-projection: the epilogue's row statistics and conv weights are staged into spare LDS by LDS-DMA at the start of the tile; the epilogue has no global loads or vmcnt waits
# speedup vs baseline: 1.0057x; 1.0057x over previous
;     __device__ __forceinline__ void operator()(const f32x4 (&acc)[2][2][4][2], const Unit& u, int wr, int wc, int fr, int fq) const {
;     ...
;             for (int m = 0; m < 4; ++m) rs[ai][m] = __builtin_amdgcn_rsqf((float)ss[u.pm * BM + ai * HALF + wr * 64 + m * 16 + fr] * (1.f / (2048.f * 262144.f)) + 1e-6f);
; #pragma unroll
;         for (int n = 0; n < 2; ++n) {
;             const int cbase = 128 * u.pn + 32 * wc + 16 * n + 4 * fq;
;             const f32x4 w0 = *(const f32x4*)(cw + cbase), w1 = *(const f32x4*)(cw + FF + cbase), w2 = *(const f32x4*)(cw + 2 * FF + cbase), b4 = *(const f32x4*)(cb + cbase);
; template <class Epi, class Sched, bool ALIGN_EPI = false, bool SP2 = false>
; __device__ __forceinline__ void gemm_phase(PG8_LAS unsigned char* lds, const Gemm g, const Sched& S, const Epi& E) {
;     ...
;     for (;;) {
;         const bool has_next = S.next(ui + 1, nxt);
;         const char* nA = has_next ? (const char*)g.A + (size_t)nxt.pm * tstep : cA; const char* nB = has_next ? (const char*)g.Bt + (size_t)nxt.pn * tstep : cB;
;         for (int t = 0; t < nt; t += 2) {
;             const bool last = (t == nt - 2);
;             const char* a1 = cA + (size_t)(t + 1) * kstep;
;             const char* a2 = last ? nA : cA + (size_t)(t + 2) * kstep; const char* b2 = last ? nB : cB + (size_t)(t + 2) * kstep;
;             const char* a3 = a2 + kstep; const char* b3 = b2 + kstep;
;             if (last && has_next) S.a_ready(nxt);
.LBB0_37:
	v_readfirstlane_b32 s98, v227
	s_lshr_b32 s98, s98, 6
	s_cmp_gt_u32 s98, 3
	s_cbranch_scc1 .Lstg_done
	s_and_b32 s99, s65, 1
	s_lshl_b32 s99, s99, 12
	s_add_i32 s99, s99, 0x20000
	s_lshl_b32 s100, s98, 10
	s_add_i32 s99, s99, s100
	v_and_b32_e32 v220, 63, v227
	v_mov_b32_e32 v219, 0
	s_cmp_gt_u32 s98, 1
	s_cbranch_scc1 .Lstg_w
	s_lshl_b32 s100, s66, 8
	s_lshl_b32 s101, s98, 7
	s_add_i32 s100, s100, s101
	s_lshl_b32 s100, s100, 3
	v_lshl_add_u32 v218, v220, 4, s100
	s_nop 0
	v_lshl_add_u64 v[218:219], v[218:219], 0, s[56:57]
	s_branch .Lstg_issue
.Lstg_w:
	s_lshl_b32 s100, s64, 9
	v_and_b32_e32 v221, 31, v220
	v_lshl_add_u32 v218, v221, 4, s100
	v_cmp_gt_u32_e64 s[100:101], 32, v220
	s_cmp_eq_u32 s98, 2
	s_cbranch_scc0 .Lstg_w3
	v_mov_b32_e32 v220, s60
	v_mov_b32_e32 v221, s61
	v_mov_b32_e32 v222, s52
	v_mov_b32_e32 v223, s53
	s_branch .Lstg_sel
.Lstg_w3:
	v_mov_b32_e32 v220, s54
	v_mov_b32_e32 v221, s55
	v_mov_b32_e32 v222, s62
	v_mov_b32_e32 v223, s63
.Lstg_sel:
	s_nop 1
	v_cndmask_b32_e64 v220, v220, v222, s[100:101]
	v_cndmask_b32_e64 v221, v221, v223, s[100:101]
	s_nop 0
	v_lshl_add_u64 v[218:219], v[218:219], 0, v[220:221]
.Lstg_issue:
	s_mov_b32 m0, s99
	s_nop 0
	global_load_lds_dwordx4 v[218:219], off

; __device__ __forceinline__ int otid() { int t = threadIdx.x; asm volatile("" : "+v"(t)); return t; }
;     __device__ __forceinline__ void operator()(const f32x4 (&acc)[2][2][4][2], const Unit& u, int wr, int wc, int fr, int fq) const {
;     ...
;         const int lane = otid() & 63;
;         const int src1 = (lane & 48) | ((fr + 15) & 15), src2 = (lane & 48) | ((fr + 14) & 15);
;         float rs[2][4];
; #pragma unroll
;         for (int ai = 0; ai < 2; ++ai)
; #pragma unroll
;             for (int m = 0; m < 4; ++m) rs[ai][m] = __builtin_amdgcn_rsqf((float)ss[u.pm * BM + ai * HALF + wr * 64 + m * 16 + fr] * (1.f / (2048.f * 262144.f)) + 1e-6f);
; #pragma unroll
;         for (int n = 0; n < 2; ++n) {
;             const int cbase = 128 * u.pn + 32 * wc + 16 * n + 4 * fq;
;             const f32x4 w0 = *(const f32x4*)(cw + cbase), w1 = *(const f32x4*)(cw + FF + cbase), w2 = *(const f32x4*)(cw + 2 * FF + cbase), b4 = *(const f32x4*)(cb + cbase);
; #pragma unroll
;             for (int ai = 0; ai < 2; ++ai) {
;                 const int slab = u.pm * 4 + 2 * ai + wr;
;                 f32x4 r1p = (f32x4){0.f, 0.f, 0.f, 0.f}, r2p = (f32x4){0.f, 0.f, 0.f, 0.f};
; #pragma unroll
;                 for (int m = 0; m < 4; ++m) {
;                     const f32x4 g = acc[ai][1][m][n] * rs[ai][m], v = acc[ai][0][m][n] * rs[ai][m];
;                     f32x4 r1, r2, a;
; #pragma unroll
;                     for (int e = 0; e < 4; ++e) { r1[e] = __shfl(g[e], src1); r2[e] = __shfl(g[e], src2); }
; #pragma unroll
;                     for (int e = 0; e < 4; ++e) {
;                         const float p1 = fr >= 1 ? r1[e] : r1p[e], p2 = fr >= 2 ? r2[e] : r2p[e];
;                         const float gg = b4[e] + w0[e] * p2 + w1[e] * p1 + w2[e] * g[e];
;                         a[e] = gg * __builtin_amdgcn_rcpf(1.f + __expf(-gg)) * v[e];
.LBB0_41:
	v_lshl_add_u32 v160, s66, 8, v193
	v_ashrrev_i32_e32 v161, 31, v160
	v_mov_b32_e32 v148, v227
	v_bfe_u32 v205, v227, 4, 1
	v_mul_u32_u24_e32 v205, 24, v205
	s_and_b32 s98, s65, 1
	s_lshl_b32 s98, s98, 12
	s_add_i32 s98, s98, 0x20000
	s_add_i32 s99, s98, 0x800
	v_lshl_add_u32 v114, v193, 3, s98
	ds_read_b64 v[146:147], v114
	v_lshl_or_b32 v156, s64, 7, v198
	v_ashrrev_i32_e32 v157, 31, v156
	ds_read_b64 v[190:191], v114 offset:128
	ds_read_b64 v[188:189], v114 offset:256
	ds_read_b64 v[186:187], v114 offset:384
	ds_read_b64 v[176:177], v114 offset:1024
	ds_read_b64 v[174:175], v114 offset:1152
	ds_read_b64 v[172:173], v114 offset:1280
	ds_read_b64 v[170:171], v114 offset:1408
	v_lshlrev_b64 v[158:159], 2, v[156:157]
	v_lshl_add_u32 v166, v198, 2, s99
	v_lshl_add_u64 v[118:119], s[60:61], 0, v[158:159]
	v_lshl_add_u64 v[120:121], s[62:63], 0, v[158:159]
	v_lshl_add_u64 v[164:165], s[54:55], 0, v[158:159]
	ds_read_b128 v[114:117], v166
	ds_read_b128 v[138:141], v166 offset:512
	ds_read_b128 v[130:133], v166 offset:1024
	s_nop 0
	ds_read_b128 v[118:121], v166 offset:1536
	s_waitcnt lgkmcnt(0)
	v_ffbh_u32_e32 v149, v147
	v_min_u32_e32 v149, 32, v149
	v_lshlrev_b64 v[146:147], v149, v[146:147]
	v_min_u32_e32 v146, 1, v146
	v_or_b32_e32 v146, v147, v146
	v_cvt_f32_u32_e32 v146, v146
	v_sub_u32_e32 v149, 32, v149
	v_and_b32_e32 v147, 48, v148
	v_or3_b32 v148, v147, v195, v236
	v_ldexp_f32 v146, v146, v149
	v_fmamk_f32 v146, v146, 0x31000000, v232
	v_rsq_f32_e32 v162, v146
	v_or3_b32 v146, v147, v196, v236
	v_lshlrev_b32_e32 v200, 2, v146
	v_lshlrev_b32_e32 v161, 2, v148
	v_pk_mul_f32 v[146:147], v[134:135], v[162:163] op_sel_hi:[1,0]
	v_pk_mul_f32 v[148:149], v[136:137], v[162:163] op_sel_hi:[1,0]
	s_nop 1
	v_mov_b32_dpp v163, v146 row_ror:2 row_mask:0xf bank_mask:0xf
	v_mov_b32_dpp v179, v146 row_ror:1 row_mask:0xf bank_mask:0xf
	v_mov_b32_dpp v181, v147 row_ror:1 row_mask:0xf bank_mask:0xf
	v_mov_b32_dpp v201, v147 row_ror:2 row_mask:0xf bank_mask:0xf
	v_mov_b32_dpp v183, v148 row_ror:1 row_mask:0xf bank_mask:0xf
	v_mov_b32_dpp v202, v148 row_ror:2 row_mask:0xf bank_mask:0xf
	v_mov_b32_dpp v185, v149 row_ror:1 row_mask:0xf bank_mask:0xf
	v_mov_b32_dpp v203, v149 row_ror:2 row_mask:0xf bank_mask:0xf
	s_waitcnt lgkmcnt(7)
	v_pk_mul_f32 v[136:137], v[144:145], v[162:163] op_sel_hi:[1,0]
	v_pk_mul_f32 v[134:135], v[142:143], v[162:163] op_sel_hi:[1,0]
	s_and_saveexec_b64 s[10:11], s[42:43]
	s_xor_b64 s[10:11], exec, s[10:11]
	s_movk_i32 s17, 0x2b00
	s_movk_i32 s84, 0x300
	s_mov_b32 s86, 0x24000
	s_mov_b32 s88, 0x48800000
	s_cbranch_execz .LBB0_43
	v_mov_b32_e32 v142, v149
	v_mov_b32_e32 v143, v141
	v_mov_b32_e32 v184, v133
	s_waitcnt lgkmcnt(1)
	v_pk_mul_f32 v[142:143], v[142:143], v[184:185]
	s_waitcnt lgkmcnt(0)
	v_fma_f32 v144, v117, v203, v121
	v_add_f32_e32 v143, v143, v144
	v_add_f32_e32 v142, v142, v143
	v_mul_f32_e32 v143, 0xbfb8aa3b, v142
	v_exp_f32_e32 v143, v143
	v_mov_b32_e32 v149, v140
	v_mov_b32_e32 v182, v132
	v_mov_b32_e32 v180, v131
	v_add_f32_e32 v143, 1.0, v143
	v_rcp_f32_e32 v143, v143
	v_mov_b32_e32 v178, v130
	v_mul_f32_e32 v142, v142, v143
	v_mul_f32_e32 v144, v137, v142
	v_pk_mul_f32 v[142:143], v[148:149], v[182:183]
	v_fma_f32 v137, v116, v202, v120
	v_add_f32_e32 v137, v143, v137
	v_add_f32_e32 v137, v142, v137
	v_mul_f32_e32 v142, 0xbfb8aa3b, v137
	v_exp_f32_e32 v142, v142
	v_fma_f32 v143, v115, v201, v119
	v_add_f32_e32 v142, 1.0, v142
	v_rcp_f32_e32 v142, v142
	s_nop 0
	v_mul_f32_e32 v137, v137, v142
	v_mul_f32_e32 v142, v136, v137
	v_mov_b32_e32 v136, v147
	v_mov_b32_e32 v137, v139
	v_pk_mul_f32 v[136:137], v[136:137], v[180:181]
	v_mov_b32_e32 v147, v138
	v_add_f32_e32 v137, v137, v143
	v_add_f32_e32 v136, v136, v137
	v_mul_f32_e32 v137, 0xbfb8aa3b, v136
	v_exp_f32_e32 v137, v137
	v_fma_f32 v143, v114, v163, v118
	v_add_f32_e32 v137, 1.0, v137
	v_rcp_f32_e32 v137, v137
	s_nop 0
	v_mul_f32_e32 v136, v136, v137
	v_mul_f32_e32 v135, v135, v136
	v_pk_mul_f32 v[136:137], v[146:147], v[178:179]
	s_nop 0
	v_add_f32_e32 v137, v137, v143
	v_add_f32_e32 v136, v136, v137
	v_mul_f32_e32 v137, 0xbfb8aa3b, v136
	v_exp_f32_e32 v137, v137
	s_nop 0
	v_add_f32_e32 v137, 1.0, v137
	v_rcp_f32_e32 v137, v137
	s_nop 0
	v_mul_f32_e32 v136, v136, v137
	v_mul_f32_e32 v134, v134, v136
	v_mov_b64_e32 v[136:137], s[48:49]
	v_mad_i64_i32 v[136:137], s[12:13], v160, s17, v[136:137]
	v_cvt_pk_bf16_f32 v134, v134, v135
	v_cvt_pk_bf16_f32 v135, v142, v144
	v_lshl_add_u64 v[136:137], v[156:157], 1, v[136:137]
	v_mov_b32_e32 v220, v134
	v_mov_b32_e32 v221, v135

; __device__ __forceinline__ unsigned cvt_pk_bf16(float lo, float hi) { unsigned r; asm volatile("v_cvt_pk_bf16_f32 %0, %1, %2" : "=v"(r) : "v"(lo), "v"(hi)); return r; }
;     __device__ __forceinline__ void operator()(const f32x4 (&acc)[2][2][4][2], const Unit& u, int wr, int wc, int fr, int fq) const {
;     ...
;         for (int n = 0; n < 2; ++n) {
;             const int cbase = 128 * u.pn + 32 * wc + 16 * n + 4 * fq;
;             const f32x4 w0 = *(const f32x4*)(cw + cbase), w1 = *(const f32x4*)(cw + FF + cbase), w2 = *(const f32x4*)(cw + 2 * FF + cbase), b4 = *(const f32x4*)(cb + cbase);
; #pragma unroll
;             for (int ai = 0; ai < 2; ++ai) {
;                 const int slab = u.pm * 4 + 2 * ai + wr;
;                 f32x4 r1p = (f32x4){0.f, 0.f, 0.f, 0.f}, r2p = (f32x4){0.f, 0.f, 0.f, 0.f};
; #pragma unroll
;                 for (int m = 0; m < 4; ++m) {
;                     const f32x4 g = acc[ai][1][m][n] * rs[ai][m], v = acc[ai][0][m][n] * rs[ai][m];
;                     f32x4 r1, r2, a;
; #pragma unroll
;                     for (int e = 0; e < 4; ++e) { r1[e] = __shfl(g[e], src1); r2[e] = __shfl(g[e], src2); }
; #pragma unroll
;                     for (int e = 0; e < 4; ++e) {
;                         const float p1 = fr >= 1 ? r1[e] : r1p[e], p2 = fr >= 2 ? r2[e] : r2p[e];
;                         const float gg = b4[e] + w0[e] * p2 + w1[e] * p1 + w2[e] * g[e];
;                         a[e] = gg * __builtin_amdgcn_rcpf(1.f + __expf(-gg)) * v[e];
;                     }
;                     r1p = r1; r2p = r2;
;                     const size_t row = (size_t)(u.pm * BM + ai * HALF + wr * 64 + m * 16 + fr);
;                     if (m == 0 && fr < 2) {
;                         *(f32x4*)(GF + (size_t)(slab * 2 + fr) * FF + cbase) = g; *(f32x4*)(VF + (size_t)(slab * 2 + fr) * FF + cbase) = v;
;                     } else {
;                         typedef unsigned u32x2v __attribute__((ext_vector_type(2)));
;                         u32x2v w; w.x = cvt_pk_bf16(a[0], a[1]); w.y = cvt_pk_bf16(a[2], a[3]);
;                         *(u32x2v*)(ACT + row * FF + cbase) = w;
;                     }
.LBB0_53:
	s_or_b64 exec, exec, s[10:11]
	s_nop 0
	v_or_b32_e32 v70, 16, v156
	v_ashrrev_i32_e32 v71, 31, v70
	v_lshlrev_b64 v[70:71], 2, v[70:71]
	v_lshl_add_u64 v[72:73], s[60:61], 0, v[70:71]
	v_lshl_add_u64 v[70:71], s[62:63], 0, v[70:71]
	ds_read_b128 v[66:69], v166 offset:64
	ds_read_b128 v[78:81], v166 offset:576
	ds_read_b128 v[74:77], v166 offset:1088
	s_nop 0
	ds_read_b128 v[70:73], v166 offset:1600
	v_mov_b32_e32 v163, v162
	v_mov_b32_e32 v120, v162
	v_mov_b32_e32 v121, v162
	v_pk_mul_f32 v[84:85], v[60:61], v[120:121]
	v_pk_mul_f32 v[82:83], v[58:59], v[162:163]
	s_nop 1
	v_mov_b32_dpp v101, v82 row_ror:1 row_mask:0xf bank_mask:0xf
	v_mov_b32_dpp v91, v82 row_ror:2 row_mask:0xf bank_mask:0xf
	v_mov_b32_dpp v115, v83 row_ror:1 row_mask:0xf bank_mask:0xf
	v_mov_b32_dpp v93, v83 row_ror:2 row_mask:0xf bank_mask:0xf
	v_mov_b32_dpp v117, v84 row_ror:1 row_mask:0xf bank_mask:0xf
	v_mov_b32_dpp v95, v84 row_ror:2 row_mask:0xf bank_mask:0xf
	v_mov_b32_dpp v119, v85 row_ror:1 row_mask:0xf bank_mask:0xf
	v_mov_b32_dpp v103, v85 row_ror:2 row_mask:0xf bank_mask:0xf
	v_pk_mul_f32 v[60:61], v[64:65], v[120:121]
	v_pk_mul_f32 v[58:59], v[62:63], v[162:163]
	s_and_saveexec_b64 s[10:11], s[42:43]
	s_xor_b64 s[10:11], exec, s[10:11]
	s_cbranch_execz .LBB0_55
	v_mov_b32_e32 v62, v85
	s_waitcnt lgkmcnt(0)
	v_mov_b32_e32 v63, v81
	s_waitcnt lgkmcnt(0)
	v_mov_b32_e32 v118, v77
	s_waitcnt lgkmcnt(1)
	v_pk_mul_f32 v[62:63], v[62:63], v[118:119]
	s_waitcnt lgkmcnt(0)
	v_fma_f32 v64, v69, v103, v73
	v_add_f32_e32 v63, v63, v64
	v_add_f32_e32 v62, v62, v63
	v_mul_f32_e32 v63, 0xbfb8aa3b, v62
	v_exp_f32_e32 v63, v63
	v_mov_b32_e32 v85, v80
	v_mov_b32_e32 v116, v76
	v_mov_b32_e32 v114, v75
	v_add_f32_e32 v63, 1.0, v63
	v_rcp_f32_e32 v63, v63
	v_mov_b32_e32 v100, v74
	v_mul_f32_e32 v62, v62, v63
	v_mul_f32_e32 v64, v61, v62
	v_pk_mul_f32 v[62:63], v[84:85], v[116:117]
	v_fma_f32 v61, v68, v95, v72
	v_add_f32_e32 v61, v63, v61
	v_add_f32_e32 v61, v62, v61
	v_mul_f32_e32 v62, 0xbfb8aa3b, v61
	v_exp_f32_e32 v62, v62
	v_fma_f32 v63, v67, v93, v71
	v_add_f32_e32 v62, 1.0, v62
	v_rcp_f32_e32 v62, v62
	s_nop 0
	v_mul_f32_e32 v61, v61, v62
	v_mul_f32_e32 v62, v60, v61
	v_mov_b32_e32 v60, v83
	v_mov_b32_e32 v61, v79
	v_pk_mul_f32 v[60:61], v[60:61], v[114:115]
	v_mov_b32_e32 v83, v78
	v_add_f32_e32 v61, v61, v63
	v_add_f32_e32 v60, v60, v61
	v_mul_f32_e32 v61, 0xbfb8aa3b, v60
	v_exp_f32_e32 v61, v61
	v_fma_f32 v63, v66, v91, v70
	v_add_f32_e32 v61, 1.0, v61
	v_rcp_f32_e32 v61, v61
	s_nop 0
	v_mul_f32_e32 v60, v60, v61
	v_mul_f32_e32 v59, v59, v60
	v_pk_mul_f32 v[60:61], v[82:83], v[100:101]
	s_nop 0
	v_add_f32_e32 v61, v61, v63
	v_add_f32_e32 v60, v60, v61
	v_mul_f32_e32 v61, 0xbfb8aa3b, v60
	v_exp_f32_e32 v61, v61
	s_nop 0
	v_add_f32_e32 v61, 1.0, v61
	v_rcp_f32_e32 v61, v61
	s_nop 0
	v_mul_f32_e32 v60, v60, v61
	v_mul_f32_e32 v58, v58, v60
	v_mov_b64_e32 v[60:61], s[48:49]
	v_mad_i64_i32 v[60:61], s[12:13], v160, s17, v[60:61]
	v_cvt_pk_bf16_f32 v58, v58, v59
	v_cvt_pk_bf16_f32 v59, v62, v64
	v_lshl_add_u64 v[60:61], v[156:157], 1, v[60:61]
	v_mov_b32_e32 v64, v77
	v_mov_b32_e32 v62, v75
	s_nop 1
	v_permlane16_swap_b32_e32 v220, v58
	v_permlane16_swap_b32_e32 v221, v59
	v_mov_b32_e32 v222, v58
	v_mov_b32_e32 v223, v59
	v_add_co_u32_e64 v60, s[98:99], v60, v205
	s_nop 1
	v_addc_co_u32_e64 v61, s[98:99], 0, v61, s[98:99]
	global_store_dwordx4 v[60:61], v[220:223], off nt
.LBB0_55:
	s_andn2_saveexec_b64 s[10:11], s[10:11]
	s_cbranch_execz .LBB0_57
	v_lshl_add_u64 v[62:63], v[144:145], 0, v[158:159]
	global_store_dwordx4 v[62:63], v[82:85], off offset:64
	v_lshl_add_u64 v[62:63], v[168:169], 0, v[158:159]
	global_store_dwordx4 v[62:63], v[58:61], off offset:64
	s_waitcnt lgkmcnt(0)
	v_mov_b32_e32 v62, v75
	v_mov_b32_e32 v64, v77
.LBB0_57:
	s_or_b64 exec, exec, s[10:11]
	v_mov_b32_e32 v58, v142
	v_mov_b32_e32 v59, v142
	v_pk_mul_f32 v[56:57], v[56:57], v[58:59]
	s_nop 1
	v_mov_b32_dpp v83, v57 row_ror:1 row_mask:0xf bank_mask:0xf
	v_mov_b32_dpp v114, v57 row_ror:2 row_mask:0xf bank_mask:0xf
	v_mov_b32_e32 v60, v57
	s_waitcnt lgkmcnt(0)
	v_mov_b32_e32 v61, v81
	v_pk_mul_f32 v[52:53], v[52:53], v[58:59]
	s_waitcnt lgkmcnt(1)
	v_cndmask_b32_e64 v65, v83, v119, s[40:41]
	s_waitcnt lgkmcnt(0)
	v_cndmask_b32_e64 v57, v103, v114, s[42:43]
	v_pk_mul_f32 v[60:61], v[60:61], v[64:65]
	s_waitcnt lgkmcnt(0)
	v_fma_f32 v57, v69, v57, v73
	v_add_f32_e32 v57, v61, v57
	v_add_f32_e32 v60, v60, v57
	v_mul_f32_e32 v57, 0xbfb8aa3b, v60
	v_exp_f32_e32 v57, v57
	v_mov_b32_dpp v61, v56 row_ror:1 row_mask:0xf bank_mask:0xf
	v_mov_b32_dpp v103, v56 row_ror:2 row_mask:0xf bank_mask:0xf
	v_mov_b32_e32 v143, v142
	v_add_f32_e32 v57, 1.0, v57
	v_rcp_f32_e32 v58, v57
	s_waitcnt lgkmcnt(1)
	v_cndmask_b32_e64 v77, v61, v117, s[40:41]
	v_mov_b32_e32 v57, v80
	s_waitcnt lgkmcnt(0)
	v_cndmask_b32_e64 v59, v95, v103, s[42:43]
	v_pk_mul_f32 v[56:57], v[56:57], v[76:77]
	v_fma_f32 v59, v68, v59, v72
	v_add_f32_e32 v57, v57, v59
	v_add_f32_e32 v59, v56, v57
	v_pk_mul_f32 v[54:55], v[54:55], v[142:143]
	v_mul_f32_e32 v56, 0xbfb8aa3b, v59
	s_nop 1
	v_mov_b32_dpp v85, v55 row_ror:1 row_mask:0xf bank_mask:0xf
	v_mov_b32_dpp v100, v55 row_ror:2 row_mask:0xf bank_mask:0xf
	v_exp_f32_e32 v56, v56
	v_mul_f32_e32 v57, v60, v58
	v_mov_b32_dpp v82, v54 row_ror:1 row_mask:0xf bank_mask:0xf
	v_mov_b32_dpp v84, v54 row_ror:2 row_mask:0xf bank_mask:0xf
	v_add_f32_e32 v56, 1.0, v56
	v_mul_f32_e32 v53, v53, v57
	v_rcp_f32_e32 v58, v56
	s_waitcnt lgkmcnt(3)
	v_cndmask_b32_e64 v63, v85, v115, s[40:41]
	v_mov_b32_e32 v56, v55
	v_mov_b32_e32 v57, v79
	s_waitcnt lgkmcnt(2)
; __device__ __forceinline__ unsigned cvt_pk_bf16(float lo, float hi) { unsigned r; asm volatile("v_cvt_pk_bf16_f32 %0, %1, %2" : "=v"(r) : "v"(lo), "v"(hi)); return r; }
;     __device__ __forceinline__ void operator()(const f32x4 (&acc)[2][2][4][2], const Unit& u, int wr, int wc, int fr, int fq) const {
;     ...
;                 for (int m = 0; m < 4; ++m) {
;                     const f32x4 g = acc[ai][1][m][n] * rs[ai][m], v = acc[ai][0][m][n] * rs[ai][m];
;                     f32x4 r1, r2, a;
; #pragma unroll
;                     for (int e = 0; e < 4; ++e) { r1[e] = __shfl(g[e], src1); r2[e] = __shfl(g[e], src2); }
; #pragma unroll
;                     for (int e = 0; e < 4; ++e) {
;                         const float p1 = fr >= 1 ? r1[e] : r1p[e], p2 = fr >= 2 ? r2[e] : r2p[e];
;                         const float gg = b4[e] + w0[e] * p2 + w1[e] * p1 + w2[e] * g[e];
;                         a[e] = gg * __builtin_amdgcn_rcpf(1.f + __expf(-gg)) * v[e];
;                     }
;                     r1p = r1; r2p = r2;
;                     const size_t row = (size_t)(u.pm * BM + ai * HALF + wr * 64 + m * 16 + fr);
;                     if (m == 0 && fr < 2) {
;                         *(f32x4*)(GF + (size_t)(slab * 2 + fr) * FF + cbase) = g; *(f32x4*)(VF + (size_t)(slab * 2 + fr) * FF + cbase) = v;
;                     } else {
;                         typedef unsigned u32x2v __attribute__((ext_vector_type(2)));
;                         u32x2v w; w.x = cvt_pk_bf16(a[0], a[1]); w.y = cvt_pk_bf16(a[2], a[3]);
;                         *(u32x2v*)(ACT + row * FF + cbase) = w;
	v_cndmask_b32_e64 v55, v93, v100, s[42:43]
	v_pk_mul_f32 v[56:57], v[56:57], v[62:63]
	v_fma_f32 v55, v67, v55, v71
	v_add_f32_e32 v55, v57, v55
	v_add_f32_e32 v56, v56, v55
	v_mul_f32_e32 v55, 0xbfb8aa3b, v56
	v_exp_f32_e32 v57, v55
	s_waitcnt lgkmcnt(1)
	v_cndmask_b32_e64 v75, v82, v101, s[40:41]
	v_mov_b32_e32 v55, v78
	s_waitcnt lgkmcnt(0)
	v_cndmask_b32_e64 v60, v91, v84, s[42:43]
	v_pk_mul_f32 v[54:55], v[54:55], v[74:75]
	v_fma_f32 v60, v66, v60, v70
	v_add_f32_e32 v55, v55, v60
	v_add_f32_e32 v54, v54, v55
	v_mul_f32_e32 v55, 0xbfb8aa3b, v54
	v_exp_f32_e32 v55, v55
	v_add_f32_e32 v57, 1.0, v57
	v_rcp_f32_e32 v57, v57
	v_pk_mul_f32 v[50:51], v[50:51], v[142:143]
	v_add_f32_e32 v55, 1.0, v55
	v_rcp_f32_e32 v55, v55
	v_mul_f32_e32 v56, v56, v57
	v_mul_f32_e32 v58, v59, v58
	v_mul_f32_e32 v51, v51, v56
	v_mul_f32_e32 v54, v54, v55
	v_mul_f32_e32 v50, v50, v54
	v_mul_f32_e32 v52, v52, v58
	v_cvt_pk_bf16_f32 v50, v50, v51
	v_cvt_pk_bf16_f32 v51, v52, v53
	s_nop 1
	v_permlane16_swap_b32_e32 v206, v50
	v_permlane16_swap_b32_e32 v207, v51
	v_mov_b32_e32 v220, v206
	v_mov_b32_e32 v221, v207
	v_mov_b32_e32 v222, v50
	v_mov_b32_e32 v223, v51
	v_add_co_u32_e64 v122, s[98:99], v122, v205
	s_nop 1
	v_addc_co_u32_e64 v123, s[98:99], 0, v123, s[98:99]
	global_store_dwordx4 v[122:123], v[220:223], off nt
	v_mov_b32_e32 v50, v136
	v_mov_b32_e32 v51, v136
	v_pk_mul_f32 v[48:49], v[48:49], v[50:51]
	s_nop 1
	v_mov_b32_dpp v55, v49 row_ror:1 row_mask:0xf bank_mask:0xf
	v_mov_b32_dpp v59, v49 row_ror:2 row_mask:0xf bank_mask:0xf
	v_mov_b32_e32 v52, v49
	v_mov_b32_e32 v53, v81
	v_mov_b32_dpp v60, v48 row_ror:2 row_mask:0xf bank_mask:0xf
	s_waitcnt lgkmcnt(2)
	v_cndmask_b32_e64 v65, v55, v83, s[40:41]
	s_waitcnt lgkmcnt(1)
	v_cndmask_b32_e64 v49, v114, v59, s[42:43]
	v_pk_mul_f32 v[52:53], v[52:53], v[64:65]
	v_fma_f32 v49, v69, v49, v73
	v_add_f32_e32 v49, v53, v49
	v_add_f32_e32 v52, v52, v49
	v_mul_f32_e32 v49, 0xbfb8aa3b, v52
	v_exp_f32_e32 v49, v49
	v_mov_b32_dpp v53, v48 row_ror:1 row_mask:0xf bank_mask:0xf
	v_pk_mul_f32 v[44:45], v[44:45], v[50:51]
	s_waitcnt lgkmcnt(1)
	v_cndmask_b32_e64 v51, v103, v60, s[42:43]
	v_add_f32_e32 v49, 1.0, v49
	v_rcp_f32_e32 v50, v49
	s_waitcnt lgkmcnt(0)
	v_cndmask_b32_e64 v77, v53, v61, s[40:41]
	v_mov_b32_e32 v49, v80
	v_pk_mul_f32 v[48:49], v[48:49], v[76:77]
	v_fma_f32 v51, v68, v51, v72
	v_add_f32_e32 v49, v49, v51
	v_mov_b32_e32 v137, v136
	v_add_f32_e32 v51, v48, v49
	v_pk_mul_f32 v[46:47], v[46:47], v[136:137]
	v_mul_f32_e32 v48, 0xbfb8aa3b, v51
	s_nop 1
	v_mov_b32_dpp v57, v47 row_ror:1 row_mask:0xf bank_mask:0xf
	v_mov_b32_dpp v58, v47 row_ror:2 row_mask:0xf bank_mask:0xf
	v_exp_f32_e32 v48, v48
	v_mul_f32_e32 v49, v52, v50
	v_mov_b32_dpp v54, v46 row_ror:1 row_mask:0xf bank_mask:0xf
	v_mov_b32_dpp v56, v46 row_ror:2 row_mask:0xf bank_mask:0xf
	v_add_f32_e32 v48, 1.0, v48
	v_mul_f32_e32 v45, v45, v49
	v_rcp_f32_e32 v50, v48
	s_waitcnt lgkmcnt(3)
	v_cndmask_b32_e64 v63, v57, v85, s[40:41]
	v_mov_b32_e32 v48, v47
	v_mov_b32_e32 v49, v79
	s_waitcnt lgkmcnt(2)
	v_cndmask_b32_e64 v47, v100, v58, s[42:43]
	v_pk_mul_f32 v[48:49], v[48:49], v[62:63]
	v_fma_f32 v47, v67, v47, v71
	v_add_f32_e32 v47, v49, v47
	v_add_f32_e32 v48, v48, v47
	v_mul_f32_e32 v47, 0xbfb8aa3b, v48
	v_exp_f32_e32 v49, v47
	s_waitcnt lgkmcnt(1)
	v_cndmask_b32_e64 v75, v54, v82, s[40:41]
	v_mov_b32_e32 v47, v78
	s_waitcnt lgkmcnt(0)
; __device__ __forceinline__ unsigned cvt_pk_bf16(float lo, float hi) { unsigned r; asm volatile("v_cvt_pk_bf16_f32 %0, %1, %2" : "=v"(r) : "v"(lo), "v"(hi)); return r; }
;     __device__ __forceinline__ void operator()(const f32x4 (&acc)[2][2][4][2], const Unit& u, int wr, int wc, int fr, int fq) const {
;     ...
;                 for (int m = 0; m < 4; ++m) {
;                     const f32x4 g = acc[ai][1][m][n] * rs[ai][m], v = acc[ai][0][m][n] * rs[ai][m];
;                     f32x4 r1, r2, a;
; #pragma unroll
;                     for (int e = 0; e < 4; ++e) { r1[e] = __shfl(g[e], src1); r2[e] = __shfl(g[e], src2); }
; #pragma unroll
;                     for (int e = 0; e < 4; ++e) {
;                         const float p1 = fr >= 1 ? r1[e] : r1p[e], p2 = fr >= 2 ? r2[e] : r2p[e];
;                         const float gg = b4[e] + w0[e] * p2 + w1[e] * p1 + w2[e] * g[e];
;                         a[e] = gg * __builtin_amdgcn_rcpf(1.f + __expf(-gg)) * v[e];
;                     }
;                     r1p = r1; r2p = r2;
;                     const size_t row = (size_t)(u.pm * BM + ai * HALF + wr * 64 + m * 16 + fr);
;                     if (m == 0 && fr < 2) {
;                         *(f32x4*)(GF + (size_t)(slab * 2 + fr) * FF + cbase) = g; *(f32x4*)(VF + (size_t)(slab * 2 + fr) * FF + cbase) = v;
;                     } else {
;                         typedef unsigned u32x2v __attribute__((ext_vector_type(2)));
;                         u32x2v w; w.x = cvt_pk_bf16(a[0], a[1]); w.y = cvt_pk_bf16(a[2], a[3]);
;                         *(u32x2v*)(ACT + row * FF + cbase) = w;
;                     }
;                     if (m == 3 && fr >= 14) *(f32x4*)(GL + (size_t)(slab * 2 + fr - 14) * FF + cbase) = g;
	v_cndmask_b32_e64 v52, v84, v56, s[42:43]
	v_pk_mul_f32 v[46:47], v[46:47], v[74:75]
	v_fma_f32 v52, v66, v52, v70
	v_add_f32_e32 v47, v47, v52
	v_add_f32_e32 v46, v46, v47
	v_mul_f32_e32 v47, 0xbfb8aa3b, v46
	v_exp_f32_e32 v47, v47
	v_add_f32_e32 v49, 1.0, v49
	v_rcp_f32_e32 v49, v49
	v_pk_mul_f32 v[42:43], v[42:43], v[136:137]
	v_add_f32_e32 v47, 1.0, v47
	v_rcp_f32_e32 v47, v47
	v_mul_f32_e32 v48, v48, v49
	v_mul_f32_e32 v50, v51, v50
	v_mul_f32_e32 v43, v43, v48
	v_mul_f32_e32 v46, v46, v47
	v_mul_f32_e32 v42, v42, v46
	v_mul_f32_e32 v44, v44, v50
	v_cvt_pk_bf16_f32 v42, v42, v43
	v_cvt_pk_bf16_f32 v43, v44, v45
	s_nop 1
	v_permlane16_swap_b32_e32 v208, v42
	v_permlane16_swap_b32_e32 v209, v43
	v_mov_b32_e32 v220, v208
	v_mov_b32_e32 v221, v209
	v_mov_b32_e32 v222, v42
	v_mov_b32_e32 v223, v43
	v_add_co_u32_e64 v108, s[98:99], v108, v205
	s_nop 1
	v_addc_co_u32_e64 v109, s[98:99], 0, v109, s[98:99]
	global_store_dwordx4 v[108:109], v[220:223], off nt
	v_mov_b32_e32 v42, v134
	v_mov_b32_e32 v43, v134
	v_pk_mul_f32 v[40:41], v[40:41], v[42:43]
	s_nop 1
	v_mov_b32_dpp v44, v41 row_ror:1 row_mask:0xf bank_mask:0xf
	v_mov_b32_dpp v50, v41 row_ror:2 row_mask:0xf bank_mask:0xf
	v_mov_b32_e32 v45, v81
	v_mov_b32_dpp v51, v40 row_ror:2 row_mask:0xf bank_mask:0xf
	v_pk_mul_f32 v[36:37], v[36:37], v[42:43]
	s_waitcnt lgkmcnt(2)
	v_cndmask_b32_e64 v65, v44, v55, s[40:41]
	v_mov_b32_e32 v44, v41
	s_waitcnt lgkmcnt(1)
	v_cndmask_b32_e64 v50, v59, v50, s[42:43]
	v_pk_mul_f32 v[44:45], v[44:45], v[64:65]
	v_fma_f32 v50, v69, v50, v73
	v_add_f32_e32 v45, v45, v50
	v_add_f32_e32 v44, v44, v45
	v_mul_f32_e32 v45, 0xbfb8aa3b, v44
	v_exp_f32_e32 v45, v45
	v_mov_b32_dpp v50, v40 row_ror:1 row_mask:0xf bank_mask:0xf
	v_mov_b32_e32 v43, v80
	v_mov_b32_e32 v135, v134
	v_add_f32_e32 v42, 1.0, v45
	v_rcp_f32_e32 v45, v42
	s_waitcnt lgkmcnt(0)
	v_cndmask_b32_e64 v77, v50, v53, s[40:41]
	v_mov_b32_e32 v42, v40
	v_cndmask_b32_e64 v50, v60, v51, s[42:43]
	v_pk_mul_f32 v[42:43], v[42:43], v[76:77]
	v_fma_f32 v50, v68, v50, v72
	v_add_f32_e32 v43, v43, v50
	v_add_f32_e32 v50, v42, v43
	v_pk_mul_f32 v[38:39], v[38:39], v[134:135]
	v_mul_f32_e32 v42, 0xbfb8aa3b, v50
	s_nop 1
	v_mov_b32_dpp v48, v39 row_ror:1 row_mask:0xf bank_mask:0xf
	v_mov_b32_dpp v49, v39 row_ror:2 row_mask:0xf bank_mask:0xf
	v_exp_f32_e32 v42, v42
	v_mul_f32_e32 v43, v44, v45
	v_mov_b32_dpp v46, v38 row_ror:1 row_mask:0xf bank_mask:0xf
	v_mov_b32_dpp v47, v38 row_ror:2 row_mask:0xf bank_mask:0xf
	v_add_f32_e32 v42, 1.0, v42
	v_mul_f32_e32 v37, v37, v43
	v_rcp_f32_e32 v44, v42
	s_waitcnt lgkmcnt(3)
	v_cndmask_b32_e64 v63, v48, v57, s[40:41]
	v_mov_b32_e32 v42, v39
	v_mov_b32_e32 v43, v79
	s_waitcnt lgkmcnt(2)
	v_cndmask_b32_e64 v45, v58, v49, s[42:43]
	v_pk_mul_f32 v[42:43], v[42:43], v[62:63]
	v_fma_f32 v45, v67, v45, v71
	v_add_f32_e32 v43, v43, v45
	v_add_f32_e32 v45, v42, v43
	v_mul_f32_e32 v42, 0xbfb8aa3b, v45
	v_exp_f32_e32 v48, v42
	s_waitcnt lgkmcnt(1)
	v_cndmask_b32_e64 v75, v46, v54, s[40:41]
	v_mov_b32_e32 v42, v38
	v_mov_b32_e32 v43, v78
	s_waitcnt lgkmcnt(0)
	v_cndmask_b32_e64 v46, v56, v47, s[42:43]
	v_pk_mul_f32 v[42:43], v[42:43], v[74:75]
	v_fma_f32 v46, v66, v46, v70
	v_add_f32_e32 v43, v43, v46
	v_add_f32_e32 v42, v42, v43
	v_mul_f32_e32 v43, 0xbfb8aa3b, v42
	v_exp_f32_e32 v43, v43
	v_add_f32_e32 v46, 1.0, v48
	v_rcp_f32_e32 v46, v46
	v_mul_f32_e32 v44, v50, v44
	v_add_f32_e32 v43, 1.0, v43
	v_rcp_f32_e32 v43, v43
	v_pk_mul_f32 v[34:35], v[34:35], v[134:135]
	v_mul_f32_e32 v36, v36, v44
	v_mul_f32_e32 v44, v45, v46
	v_mul_f32_e32 v42, v42, v43
	v_mul_f32_e32 v35, v35, v44
	v_mul_f32_e32 v34, v34, v42
	v_cvt_pk_bf16_f32 v34, v34, v35
	v_cvt_pk_bf16_f32 v35, v36, v37
	s_nop 1
	v_permlane16_swap_b32_e32 v210, v34
	v_permlane16_swap_b32_e32 v211, v35
	v_mov_b32_e32 v220, v210
	v_mov_b32_e32 v221, v211
	v_mov_b32_e32 v222, v34
	v_mov_b32_e32 v223, v35
	v_add_co_u32_e64 v110, s[98:99], v110, v205
	s_nop 1
	v_addc_co_u32_e64 v111, s[98:99], 0, v111, s[98:99]
	global_store_dwordx4 v[110:111], v[220:223], off nt
	s_and_saveexec_b64 s[10:11], s[44:45]
	s_cbranch_execz .LBB0_59
	global_store_dwordx4 v[106:107], v[38:41], off offset:64
